# prologue x -> bf16 conversion software-pipelined for the 256-workgroup grid (8-16 loads per lane in flight, loads issued ahead of the previous group's stores)
# baseline (speedup 1.0000x reference)
; __device__ __forceinline__ int otid(int wv0) { int t = (wv0 << 6) | olane(); asm volatile("" : "+v"(t)); return t; }
; __device__ __forceinline__ int obid() { int b = blockIdx.x; asm volatile("" : "+s"(b)); return b; }
; __device__ __forceinline__ int ogrid() { int g = gridDim.x; asm volatile("" : "+s"(g)); return g; }
; __device__ __forceinline__ void prologue(KP p, int wv0) {
;   const size_t tid = (size_t)obid() * 512 + otid(wv0), nth = (size_t)ogrid() * 512;
;   bf16_t* xb = (bf16_t*)(p->ws + O_XB);
;   for (size_t i = tid; i < (size_t)NTOK * DM / 4; i += 4 * nth) {
;     f32x4 v[4];
; #pragma unroll
;     for (int j = 0; j < 4; ++j) if (i + j * nth < (size_t)NTOK * DM / 4) v[j] = ((const f32x4*)p->x)[i + j * nth];
; #pragma unroll
;     for (int j = 0; j < 4; ++j) if (i + j * nth < (size_t)NTOK * DM / 4) { u32x2 w; w.x = pk2(v[j][0], v[j][1]); w.y = pk2(v[j][2], v[j][3]); ((u32x2*)xb)[i + j * nth] = w; } }
.LBB0_106:
	s_mov_b32 s12, s82
	s_mov_b32 s1, -1
	s_ashr_i32 s13, s12, 31
	s_waitcnt vmcnt(1)
	v_mbcnt_lo_u32_b32 v1, s1, 0
	v_mbcnt_hi_u32_b32 v1, s1, v1
	v_or_b32_e32 v20, s0, v1
	s_waitcnt lgkmcnt(0)
	s_lshl_b64 s[2:3], s[12:13], 9
	s_mov_b32 s14, s60
	v_ashrrev_i32_e32 v21, 31, v20
	v_lshl_add_u64 v[18:19], s[2:3], 0, v[20:21]
	s_ashr_i32 s15, s14, 31
	s_mov_b64 s[16:17], 0x800000
	s_lshl_b64 s[10:11], s[14:15], 9
	v_cmp_gt_u64_e32 vcc, s[16:17], v[18:19]
	s_and_saveexec_b64 s[18:19], vcc
	s_cbranch_execz .LBB0_121
	s_cmp_eq_u32 s60, 0x100
	s_cbranch_scc0 .Lx2b_orig
	s_load_dwordx2 s[20:21], s[54:55], 0x0
	v_lshlrev_b32_e32 v64, 4, v18
	v_lshlrev_b32_e32 v72, 3, v18
	v_add_u32_e32 v65, 0x200000, v64
	v_add_u32_e32 v73, 0x100000, v72
	v_add_u32_e32 v66, 0x400000, v64
	v_add_u32_e32 v74, 0x200000, v72
	v_add_u32_e32 v67, 0x600000, v64
	v_add_u32_e32 v75, 0x300000, v72
	v_add_u32_e32 v68, 0x800000, v64
	v_add_u32_e32 v76, 0x400000, v72
	v_add_u32_e32 v69, 0xa00000, v64
	v_add_u32_e32 v77, 0x500000, v72
	v_add_u32_e32 v70, 0xc00000, v64
	v_add_u32_e32 v78, 0x600000, v72
	v_add_u32_e32 v71, 0xe00000, v64
	v_add_u32_e32 v79, 0x700000, v72
	s_add_u32 s22, s8, 0x4900000
	s_addc_u32 s23, s9, 0
	s_waitcnt lgkmcnt(0)
	s_add_u32 s24, s20, 0x0
	s_addc_u32 s25, s21, 0
	global_load_dwordx4 v[2:5], v64, s[24:25]
	global_load_dwordx4 v[6:9], v65, s[24:25]
	global_load_dwordx4 v[10:13], v66, s[24:25]
	global_load_dwordx4 v[14:17], v67, s[24:25]
	global_load_dwordx4 v[22:25], v68, s[24:25]
	global_load_dwordx4 v[26:29], v69, s[24:25]
	global_load_dwordx4 v[30:33], v70, s[24:25]
	global_load_dwordx4 v[34:37], v71, s[24:25]
	s_add_u32 s24, s20, 0x1000000
	s_addc_u32 s25, s21, 0
	global_load_dwordx4 v[48:51], v64, s[24:25]
	global_load_dwordx4 v[52:55], v65, s[24:25]
	global_load_dwordx4 v[56:59], v66, s[24:25]
	global_load_dwordx4 v[60:63], v67, s[24:25]
	global_load_dwordx4 v[100:103], v68, s[24:25]
	global_load_dwordx4 v[104:107], v69, s[24:25]
	global_load_dwordx4 v[108:111], v70, s[24:25]
	global_load_dwordx4 v[112:115], v71, s[24:25]
	s_waitcnt vmcnt(8)
	v_cvt_pk_bf16_f32 v2, v2, v3
	v_cvt_pk_bf16_f32 v3, v4, v5
	v_cvt_pk_bf16_f32 v6, v6, v7
	v_cvt_pk_bf16_f32 v7, v8, v9
	v_cvt_pk_bf16_f32 v10, v10, v11
	v_cvt_pk_bf16_f32 v11, v12, v13
	v_cvt_pk_bf16_f32 v14, v14, v15
	v_cvt_pk_bf16_f32 v15, v16, v17
	v_cvt_pk_bf16_f32 v22, v22, v23
	v_cvt_pk_bf16_f32 v23, v24, v25
	v_cvt_pk_bf16_f32 v26, v26, v27
	v_cvt_pk_bf16_f32 v27, v28, v29
	v_cvt_pk_bf16_f32 v30, v30, v31
	v_cvt_pk_bf16_f32 v31, v32, v33
	v_cvt_pk_bf16_f32 v34, v34, v35
	v_cvt_pk_bf16_f32 v35, v36, v37
	s_add_u32 s26, s22, 0x0
	s_addc_u32 s27, s23, 0
	global_store_dwordx2 v72, v[2:3], s[26:27]
	global_store_dwordx2 v73, v[6:7], s[26:27]
	global_store_dwordx2 v74, v[10:11], s[26:27]
	global_store_dwordx2 v75, v[14:15], s[26:27]
	global_store_dwordx2 v76, v[22:23], s[26:27]
	global_store_dwordx2 v77, v[26:27], s[26:27]
	global_store_dwordx2 v78, v[30:31], s[26:27]
	global_store_dwordx2 v79, v[34:35], s[26:27]
	s_add_u32 s24, s20, 0x2000000
	s_addc_u32 s25, s21, 0
	global_load_dwordx4 v[2:5], v64, s[24:25]
	global_load_dwordx4 v[6:9], v65, s[24:25]
	global_load_dwordx4 v[10:13], v66, s[24:25]
	global_load_dwordx4 v[14:17], v67, s[24:25]
	global_load_dwordx4 v[22:25], v68, s[24:25]
	global_load_dwordx4 v[26:29], v69, s[24:25]
	global_load_dwordx4 v[30:33], v70, s[24:25]
	global_load_dwordx4 v[34:37], v71, s[24:25]
	s_waitcnt vmcnt(16)
	v_cvt_pk_bf16_f32 v48, v48, v49
	v_cvt_pk_bf16_f32 v49, v50, v51
	v_cvt_pk_bf16_f32 v52, v52, v53
	v_cvt_pk_bf16_f32 v53, v54, v55
	v_cvt_pk_bf16_f32 v56, v56, v57
	v_cvt_pk_bf16_f32 v57, v58, v59
	v_cvt_pk_bf16_f32 v60, v60, v61
	v_cvt_pk_bf16_f32 v61, v62, v63
	v_cvt_pk_bf16_f32 v100, v100, v101
	v_cvt_pk_bf16_f32 v101, v102, v103
	v_cvt_pk_bf16_f32 v104, v104, v105
	v_cvt_pk_bf16_f32 v105, v106, v107
	v_cvt_pk_bf16_f32 v108, v108, v109
	v_cvt_pk_bf16_f32 v109, v110, v111
	v_cvt_pk_bf16_f32 v112, v112, v113
	v_cvt_pk_bf16_f32 v113, v114, v115
	s_add_u32 s26, s22, 0x800000
	s_addc_u32 s27, s23, 0
	global_store_dwordx2 v72, v[48:49], s[26:27]
	global_store_dwordx2 v73, v[52:53], s[26:27]
	global_store_dwordx2 v74, v[56:57], s[26:27]
	global_store_dwordx2 v75, v[60:61], s[26:27]
	global_store_dwordx2 v76, v[100:101], s[26:27]
	global_store_dwordx2 v77, v[104:105], s[26:27]
	global_store_dwordx2 v78, v[108:109], s[26:27]
	global_store_dwordx2 v79, v[112:113], s[26:27]
	s_add_u32 s24, s20, 0x3000000
	s_addc_u32 s25, s21, 0
	global_load_dwordx4 v[48:51], v64, s[24:25]
	global_load_dwordx4 v[52:55], v65, s[24:25]
	global_load_dwordx4 v[56:59], v66, s[24:25]
	global_load_dwordx4 v[60:63], v67, s[24:25]
	global_load_dwordx4 v[100:103], v68, s[24:25]
	global_load_dwordx4 v[104:107], v69, s[24:25]
	global_load_dwordx4 v[108:111], v70, s[24:25]
	global_load_dwordx4 v[112:115], v71, s[24:25]
	s_waitcnt vmcnt(16)
	v_cvt_pk_bf16_f32 v2, v2, v3
	v_cvt_pk_bf16_f32 v3, v4, v5
	v_cvt_pk_bf16_f32 v6, v6, v7
	v_cvt_pk_bf16_f32 v7, v8, v9
	v_cvt_pk_bf16_f32 v10, v10, v11
	v_cvt_pk_bf16_f32 v11, v12, v13
	v_cvt_pk_bf16_f32 v14, v14, v15
	v_cvt_pk_bf16_f32 v15, v16, v17
	v_cvt_pk_bf16_f32 v22, v22, v23
	v_cvt_pk_bf16_f32 v23, v24, v25
	v_cvt_pk_bf16_f32 v26, v26, v27
	v_cvt_pk_bf16_f32 v27, v28, v29
	v_cvt_pk_bf16_f32 v30, v30, v31
	v_cvt_pk_bf16_f32 v31, v32, v33
	v_cvt_pk_bf16_f32 v34, v34, v35
	v_cvt_pk_bf16_f32 v35, v36, v37
	s_add_u32 s26, s22, 0x1000000
	s_addc_u32 s27, s23, 0
	global_store_dwordx2 v72, v[2:3], s[26:27]
	global_store_dwordx2 v73, v[6:7], s[26:27]
	global_store_dwordx2 v74, v[10:11], s[26:27]
	global_store_dwordx2 v75, v[14:15], s[26:27]
	global_store_dwordx2 v76, v[22:23], s[26:27]
	global_store_dwordx2 v77, v[26:27], s[26:27]
	global_store_dwordx2 v78, v[30:31], s[26:27]
	global_store_dwordx2 v79, v[34:35], s[26:27]
	s_add_u32 s24, s20, 0x4000000
	s_addc_u32 s25, s21, 0
	global_load_dwordx4 v[2:5], v64, s[24:25]
	global_load_dwordx4 v[6:9], v65, s[24:25]
	global_load_dwordx4 v[10:13], v66, s[24:25]
	global_load_dwordx4 v[14:17], v67, s[24:25]
	global_load_dwordx4 v[22:25], v68, s[24:25]
	global_load_dwordx4 v[26:29], v69, s[24:25]
	global_load_dwordx4 v[30:33], v70, s[24:25]
	global_load_dwordx4 v[34:37], v71, s[24:25]
	s_waitcnt vmcnt(16)
; __device__ __forceinline__ int otid(int wv0) { int t = (wv0 << 6) | olane(); asm volatile("" : "+v"(t)); return t; }
; __device__ __forceinline__ int obid() { int b = blockIdx.x; asm volatile("" : "+s"(b)); return b; }
; __device__ __forceinline__ int ogrid() { int g = gridDim.x; asm volatile("" : "+s"(g)); return g; }
; __device__ __forceinline__ void prologue(KP p, int wv0) {
;   const size_t tid = (size_t)obid() * 512 + otid(wv0), nth = (size_t)ogrid() * 512;
;   bf16_t* xb = (bf16_t*)(p->ws + O_XB);
;   for (size_t i = tid; i < (size_t)NTOK * DM / 4; i += 4 * nth) {
;     f32x4 v[4];
; #pragma unroll
;     for (int j = 0; j < 4; ++j) if (i + j * nth < (size_t)NTOK * DM / 4) v[j] = ((const f32x4*)p->x)[i + j * nth];
; #pragma unroll
;     for (int j = 0; j < 4; ++j) if (i + j * nth < (size_t)NTOK * DM / 4) { u32x2 w; w.x = pk2(v[j][0], v[j][1]); w.y = pk2(v[j][2], v[j][3]); ((u32x2*)xb)[i + j * nth] = w; } }
	v_cvt_pk_bf16_f32 v48, v48, v49
	v_cvt_pk_bf16_f32 v49, v50, v51
	v_cvt_pk_bf16_f32 v52, v52, v53
	v_cvt_pk_bf16_f32 v53, v54, v55
	v_cvt_pk_bf16_f32 v56, v56, v57
	v_cvt_pk_bf16_f32 v57, v58, v59
	v_cvt_pk_bf16_f32 v60, v60, v61
	v_cvt_pk_bf16_f32 v61, v62, v63
	v_cvt_pk_bf16_f32 v100, v100, v101
	v_cvt_pk_bf16_f32 v101, v102, v103
	v_cvt_pk_bf16_f32 v104, v104, v105
	v_cvt_pk_bf16_f32 v105, v106, v107
	v_cvt_pk_bf16_f32 v108, v108, v109
	v_cvt_pk_bf16_f32 v109, v110, v111
	v_cvt_pk_bf16_f32 v112, v112, v113
	v_cvt_pk_bf16_f32 v113, v114, v115
	s_add_u32 s26, s22, 0x1800000
	s_addc_u32 s27, s23, 0
	global_store_dwordx2 v72, v[48:49], s[26:27]
	global_store_dwordx2 v73, v[52:53], s[26:27]
	global_store_dwordx2 v74, v[56:57], s[26:27]
	global_store_dwordx2 v75, v[60:61], s[26:27]
	global_store_dwordx2 v76, v[100:101], s[26:27]
	global_store_dwordx2 v77, v[104:105], s[26:27]
	global_store_dwordx2 v78, v[108:109], s[26:27]
	global_store_dwordx2 v79, v[112:113], s[26:27]
	s_add_u32 s24, s20, 0x5000000
	s_addc_u32 s25, s21, 0
	global_load_dwordx4 v[48:51], v64, s[24:25]
	global_load_dwordx4 v[52:55], v65, s[24:25]
	global_load_dwordx4 v[56:59], v66, s[24:25]
	global_load_dwordx4 v[60:63], v67, s[24:25]
	global_load_dwordx4 v[100:103], v68, s[24:25]
	global_load_dwordx4 v[104:107], v69, s[24:25]
	global_load_dwordx4 v[108:111], v70, s[24:25]
	global_load_dwordx4 v[112:115], v71, s[24:25]
	s_waitcnt vmcnt(16)
	v_cvt_pk_bf16_f32 v2, v2, v3
	v_cvt_pk_bf16_f32 v3, v4, v5
	v_cvt_pk_bf16_f32 v6, v6, v7
	v_cvt_pk_bf16_f32 v7, v8, v9
	v_cvt_pk_bf16_f32 v10, v10, v11
	v_cvt_pk_bf16_f32 v11, v12, v13
	v_cvt_pk_bf16_f32 v14, v14, v15
	v_cvt_pk_bf16_f32 v15, v16, v17
	v_cvt_pk_bf16_f32 v22, v22, v23
	v_cvt_pk_bf16_f32 v23, v24, v25
	v_cvt_pk_bf16_f32 v26, v26, v27
	v_cvt_pk_bf16_f32 v27, v28, v29
	v_cvt_pk_bf16_f32 v30, v30, v31
	v_cvt_pk_bf16_f32 v31, v32, v33
	v_cvt_pk_bf16_f32 v34, v34, v35
	v_cvt_pk_bf16_f32 v35, v36, v37
	s_add_u32 s26, s22, 0x2000000
	s_addc_u32 s27, s23, 0
	global_store_dwordx2 v72, v[2:3], s[26:27]
	global_store_dwordx2 v73, v[6:7], s[26:27]
	global_store_dwordx2 v74, v[10:11], s[26:27]
	global_store_dwordx2 v75, v[14:15], s[26:27]
	global_store_dwordx2 v76, v[22:23], s[26:27]
	global_store_dwordx2 v77, v[26:27], s[26:27]
	global_store_dwordx2 v78, v[30:31], s[26:27]
	global_store_dwordx2 v79, v[34:35], s[26:27]
	s_add_u32 s24, s20, 0x6000000
	s_addc_u32 s25, s21, 0
	global_load_dwordx4 v[2:5], v64, s[24:25]
	global_load_dwordx4 v[6:9], v65, s[24:25]
	global_load_dwordx4 v[10:13], v66, s[24:25]
	global_load_dwordx4 v[14:17], v67, s[24:25]
	global_load_dwordx4 v[22:25], v68, s[24:25]
	global_load_dwordx4 v[26:29], v69, s[24:25]
	global_load_dwordx4 v[30:33], v70, s[24:25]
	global_load_dwordx4 v[34:37], v71, s[24:25]
	s_waitcnt vmcnt(16)
	v_cvt_pk_bf16_f32 v48, v48, v49
	v_cvt_pk_bf16_f32 v49, v50, v51
	v_cvt_pk_bf16_f32 v52, v52, v53
	v_cvt_pk_bf16_f32 v53, v54, v55
	v_cvt_pk_bf16_f32 v56, v56, v57
	v_cvt_pk_bf16_f32 v57, v58, v59
	v_cvt_pk_bf16_f32 v60, v60, v61
	v_cvt_pk_bf16_f32 v61, v62, v63
	v_cvt_pk_bf16_f32 v100, v100, v101
	v_cvt_pk_bf16_f32 v101, v102, v103
	v_cvt_pk_bf16_f32 v104, v104, v105
	v_cvt_pk_bf16_f32 v105, v106, v107
	v_cvt_pk_bf16_f32 v108, v108, v109
	v_cvt_pk_bf16_f32 v109, v110, v111
	v_cvt_pk_bf16_f32 v112, v112, v113
	v_cvt_pk_bf16_f32 v113, v114, v115
	s_add_u32 s26, s22, 0x2800000
	s_addc_u32 s27, s23, 0
	global_store_dwordx2 v72, v[48:49], s[26:27]
	global_store_dwordx2 v73, v[52:53], s[26:27]
	global_store_dwordx2 v74, v[56:57], s[26:27]
	global_store_dwordx2 v75, v[60:61], s[26:27]
	global_store_dwordx2 v76, v[100:101], s[26:27]
	global_store_dwordx2 v77, v[104:105], s[26:27]
	global_store_dwordx2 v78, v[108:109], s[26:27]
	global_store_dwordx2 v79, v[112:113], s[26:27]
	s_add_u32 s24, s20, 0x7000000
	s_addc_u32 s25, s21, 0
	global_load_dwordx4 v[48:51], v64, s[24:25]
	global_load_dwordx4 v[52:55], v65, s[24:25]
	global_load_dwordx4 v[56:59], v66, s[24:25]
	global_load_dwordx4 v[60:63], v67, s[24:25]
	global_load_dwordx4 v[100:103], v68, s[24:25]
	global_load_dwordx4 v[104:107], v69, s[24:25]
	global_load_dwordx4 v[108:111], v70, s[24:25]
	global_load_dwordx4 v[112:115], v71, s[24:25]
	s_waitcnt vmcnt(16)
	v_cvt_pk_bf16_f32 v2, v2, v3
	v_cvt_pk_bf16_f32 v3, v4, v5
	v_cvt_pk_bf16_f32 v6, v6, v7
	v_cvt_pk_bf16_f32 v7, v8, v9
	v_cvt_pk_bf16_f32 v10, v10, v11
	v_cvt_pk_bf16_f32 v11, v12, v13
	v_cvt_pk_bf16_f32 v14, v14, v15
	v_cvt_pk_bf16_f32 v15, v16, v17
	v_cvt_pk_bf16_f32 v22, v22, v23
	v_cvt_pk_bf16_f32 v23, v24, v25
	v_cvt_pk_bf16_f32 v26, v26, v27
	v_cvt_pk_bf16_f32 v27, v28, v29
	v_cvt_pk_bf16_f32 v30, v30, v31
	v_cvt_pk_bf16_f32 v31, v32, v33
	v_cvt_pk_bf16_f32 v34, v34, v35
	v_cvt_pk_bf16_f32 v35, v36, v37
	s_add_u32 s26, s22, 0x3000000
	s_addc_u32 s27, s23, 0
	global_store_dwordx2 v72, v[2:3], s[26:27]
	global_store_dwordx2 v73, v[6:7], s[26:27]
	global_store_dwordx2 v74, v[10:11], s[26:27]
	global_store_dwordx2 v75, v[14:15], s[26:27]
	global_store_dwordx2 v76, v[22:23], s[26:27]
	global_store_dwordx2 v77, v[26:27], s[26:27]
	global_store_dwordx2 v78, v[30:31], s[26:27]
	global_store_dwordx2 v79, v[34:35], s[26:27]
	s_waitcnt vmcnt(8)
	v_cvt_pk_bf16_f32 v48, v48, v49
	v_cvt_pk_bf16_f32 v49, v50, v51
	v_cvt_pk_bf16_f32 v52, v52, v53
	v_cvt_pk_bf16_f32 v53, v54, v55
	v_cvt_pk_bf16_f32 v56, v56, v57
	v_cvt_pk_bf16_f32 v57, v58, v59
	v_cvt_pk_bf16_f32 v60, v60, v61
	v_cvt_pk_bf16_f32 v61, v62, v63
	v_cvt_pk_bf16_f32 v100, v100, v101
	v_cvt_pk_bf16_f32 v101, v102, v103
	v_cvt_pk_bf16_f32 v104, v104, v105
	v_cvt_pk_bf16_f32 v105, v106, v107
	v_cvt_pk_bf16_f32 v108, v108, v109
	v_cvt_pk_bf16_f32 v109, v110, v111
	v_cvt_pk_bf16_f32 v112, v112, v113
	v_cvt_pk_bf16_f32 v113, v114, v115
	s_add_u32 s26, s22, 0x3800000
	s_addc_u32 s27, s23, 0
	global_store_dwordx2 v72, v[48:49], s[26:27]
	global_store_dwordx2 v73, v[52:53], s[26:27]
	global_store_dwordx2 v74, v[56:57], s[26:27]
	global_store_dwordx2 v75, v[60:61], s[26:27]
	global_store_dwordx2 v76, v[100:101], s[26:27]
	global_store_dwordx2 v77, v[104:105], s[26:27]
	global_store_dwordx2 v78, v[108:109], s[26:27]
	global_store_dwordx2 v79, v[112:113], s[26:27]
	s_branch .LBB0_121
; __device__ __forceinline__ int otid(int wv0) { int t = (wv0 << 6) | olane(); asm volatile("" : "+v"(t)); return t; }
; __device__ __forceinline__ int obid() { int b = blockIdx.x; asm volatile("" : "+s"(b)); return b; }
; __device__ __forceinline__ int ogrid() { int g = gridDim.x; asm volatile("" : "+s"(g)); return g; }
; __device__ __forceinline__ void prologue(KP p, int wv0) {
;   const size_t tid = (size_t)obid() * 512 + otid(wv0), nth = (size_t)ogrid() * 512;
;   bf16_t* xb = (bf16_t*)(p->ws + O_XB);
;   for (size_t i = tid; i < (size_t)NTOK * DM / 4; i += 4 * nth) {
;     f32x4 v[4];
; #pragma unroll
;     for (int j = 0; j < 4; ++j) if (i + j * nth < (size_t)NTOK * DM / 4) v[j] = ((const f32x4*)p->x)[i + j * nth];
; #pragma unroll
;     for (int j = 0; j < 4; ++j) if (i + j * nth < (size_t)NTOK * DM / 4) { u32x2 w; w.x = pk2(v[j][0], v[j][1]); w.y = pk2(v[j][2], v[j][3]); ((u32x2*)xb)[i + j * nth] = w; } }
.Lx2b_orig:
	s_load_dwordx2 s[20:21], s[54:55], 0x0
	s_lshl_b64 s[0:1], s[12:13], 12
	s_lshl_b64 s[4:5], s[14:15], 12
	s_add_u32 s4, s0, s4
	s_addc_u32 s5, s1, s5
	s_lshl_b64 s[22:23], s[14:15], 14
	s_lshl_b64 s[24:25], s[14:15], 10
	v_lshlrev_b64 v[2:3], 3, v[20:21]
	s_waitcnt lgkmcnt(0)
	s_add_u32 s26, s20, s22
	v_lshl_add_u64 v[4:5], s[4:5], 0, v[2:3]
	v_lshl_add_u64 v[2:3], s[0:1], 0, v[2:3]
	s_addc_u32 s27, s21, s23
	s_lshl_b64 s[0:1], s[12:13], 13
	s_lshl_b64 s[28:29], s[14:15], 15
	v_lshl_add_u64 v[26:27], v[20:21], 4, s[0:1]
	s_add_u32 s0, s24, s2
	s_mov_b64 s[4:5], 0x4900000
	s_addc_u32 s1, s25, s3
	v_lshl_add_u64 v[24:25], v[2:3], 0, s[4:5]
	v_lshl_add_u64 v[2:3], s[0:1], 0, v[20:21]
	s_mul_i32 s1, s14, 0x6000
	s_mul_hi_i32 s0, s14, 0x6000
	s_add_u32 s34, s20, s1
	s_mul_i32 s30, s14, 0x600
	s_addc_u32 s35, s21, s0
	s_mul_hi_i32 s31, s14, 0x600
	s_add_u32 s0, s30, s2
	v_lshl_add_u64 v[22:23], v[4:5], 0, s[4:5]
	v_mov_b64_e32 v[4:5], 0x4900000
	s_addc_u32 s1, s31, s3
	v_lshl_add_u64 v[28:29], v[2:3], 3, v[4:5]
	v_lshl_add_u64 v[2:3], s[0:1], 0, v[20:21]
	s_lshl_b64 s[0:1], s[14:15], 13
	v_lshl_add_u64 v[30:31], v[2:3], 3, v[4:5]
	s_add_u32 s36, s20, s0
	v_mov_b32_e32 v2, 0
	s_addc_u32 s37, s21, s1
	s_mov_b64 s[38:39], 0
	s_mov_b64 s[40:41], 0x7fffff
	v_mov_b64_e32 v[34:35], v[18:19]
	v_mov_b32_e32 v3, v2
	v_mov_b32_e32 v4, v2
	v_mov_b32_e32 v5, v2
	v_mov_b32_e32 v6, v2
	v_mov_b32_e32 v7, v2
	v_mov_b32_e32 v8, v2
	s_waitcnt vmcnt(0)
	v_mov_b32_e32 v9, v2
	v_mov_b32_e32 v10, v2
	v_mov_b32_e32 v11, v2
	v_mov_b32_e32 v12, v2
	v_mov_b32_e32 v13, v2
	s_branch .LBB0_109
